# residual GEMM epilogue: 3-deep software-pipelined x-tile loads (into dead B-fragment registers), counted vmcnt, stores never waited on
# baseline (speedup 1.0000x reference)
; #define PG8_STAGE(bufoff, gbase, voff) do { _Pragma("unroll") for (int _i = 0; _i < 2; ++_i) \
;         __builtin_amdgcn_global_load_lds((const unsigned*)((const char*)(gbase) + (voff)[_i]), (PG8_LAS unsigned*)(lds + (bufoff) + ldsw + _i * 8192), 16, 0, 0); } while (0)
; #define PG8_LDA(dst, b, h) do { _Pragma("unroll") for (int m = 0; m < 4; ++m) _Pragma("unroll") for (int k = 0; k < 2; ++k) dst[m][k] = *(const PG8_LAS bf16x8*)(lds + PG8_SA(b, h) + aoff + m * 2048 + k * 1024); } while (0)
; #define PG8_LDB(dst, b, h) do { _Pragma("unroll") for (int n = 0; n < 2; ++n) _Pragma("unroll") for (int k = 0; k < 2; ++k) dst[n][k] = *(const PG8_LAS bf16x8*)(lds + PG8_SB(b, h) + boff + n * 2048 + k * 1024); } while (0)
; #define PG8_MMA(ai, bj, At, Bt) do { __builtin_amdgcn_s_setprio(1); _Pragma("unroll") for (int m = 0; m < 4; ++m) _Pragma("unroll") for (int n = 0; n < 2; ++n) _Pragma("unroll") for (int k = 0; k < 2; ++k) \
;         acc[ai][bj][m][n] = __builtin_amdgcn_mfma_f32_16x16x32_bf16(Bt[n][k], At[m][k], acc[ai][bj][m][n], 0, 0, 0); __builtin_amdgcn_s_setprio(0); } while (0)
; #define PG8_WAIT_V(n) asm volatile("s_waitcnt vmcnt(" #n ")" ::: "memory")
; #define PG8_WAIT_L(n) asm volatile("s_waitcnt lgkmcnt(" #n ")" ::: "memory")
; #define PG8_BAR __builtin_amdgcn_s_barrier()
; #define PG8_SCHED __builtin_amdgcn_sched_barrier(0)
; template <class Epi, class Sched, bool ALIGN_EPI = false, bool SP2 = false>
; __device__ __forceinline__ void gemm_phase(PG8_LAS unsigned char* lds, const Gemm g, const Sched& S, const Epi& E, const int tid) {
;     ...
;             PG8_LDB(B0, 0, 0); PG8_LDB(B1, 0, 1); PG8_SCHED; PG8_LDA(At, 0, 0); PG8_STAGE(PG8_SA(1, 1), a1 + hstep, voffA);
;             PG8_WAIT_V(8); PG8_WAIT_L(0); PG8_BAR; PG8_MMA(0, 0, At, B0); PG8_MMA(0, 1, At, B1); PG8_BAR; PG8_SCHED;
;             PG8_LDA(At, 0, 1); PG8_STAGE(PG8_SB(0, 0), b2, voffB); PG8_STAGE(PG8_SB(0, 1), b2 + hstep, voffB); PG8_STAGE(PG8_SA(0, 0), a2, voffA);
;             PG8_WAIT_V(8); PG8_WAIT_L(0); PG8_BAR; PG8_MMA(1, 0, At, B0); PG8_MMA(1, 1, At, B1); PG8_BAR; PG8_SCHED;
.LBB0_765:
	v_add_u32_e32 v135, v161, v186
	ds_read_b128 v[142:145], v135
	ds_read_b128 v[146:149], v135 offset:1024
	ds_read_b128 v[150:153], v135 offset:2048
	ds_read_b128 v[154:157], v135 offset:3072
	v_add_u32_e32 v135, v167, v186
	ds_read_b128 v[188:191], v135
	ds_read_b128 v[192:195], v135 offset:1024
	ds_read_b128 v[196:199], v135 offset:2048
	ds_read_b128 v[200:203], v135 offset:3072
	s_add_i32 s46, s16, 2
	s_add_u32 s47, s14, 0x80
	s_addc_u32 s17, s15, 0
	s_cmp_eq_u32 s37, s16
	s_cselect_b32 s16, s8, s47
	s_cselect_b32 s17, s9, s17
	s_cselect_b32 s49, s11, s45
	s_cselect_b32 s48, s10, s44
	v_add_u32_e32 v135, 0xc000, v172
	v_lshl_add_u64 v[158:159], s[14:15], 0, v[138:139]
	v_readfirstlane_b32 s47, v135
	v_add_u32_e32 v135, 0xe000, v172
	s_mov_b32 m0, s47
	v_readfirstlane_b32 s47, v135
	ds_read_b128 v[212:215], v187
	ds_read_b128 v[216:219], v187 offset:1024
	ds_read_b128 v[220:223], v187 offset:2048
	ds_read_b128 v[224:227], v187 offset:3072
	ds_read_b128 v[228:231], v187 offset:4096
	ds_read_b128 v[232:235], v187 offset:5120
	ds_read_b128 v[236:239], v187 offset:6144
	ds_read_b128 v[240:243], v187 offset:7168
	global_load_lds_dwordx4 v[158:159], off
	v_lshl_add_u64 v[158:159], s[14:15], 0, v[140:141]
	s_mov_b32 m0, s47
	s_nop 0
	global_load_lds_dwordx4 v[158:159], off
	s_waitcnt vmcnt(8)
	s_waitcnt lgkmcnt(0)
	s_barrier
	s_setprio 1
	s_waitcnt lgkmcnt(0)
	v_mfma_f32_16x16x32_bf16 v[124:127], v[142:145], v[212:215], v[124:127]
	v_mfma_f32_16x16x32_bf16 v[120:123], v[150:153], v[212:215], v[120:123]
	v_mfma_f32_16x16x32_bf16 v[108:111], v[142:145], v[220:223], v[108:111]
	v_mfma_f32_16x16x32_bf16 v[104:107], v[150:153], v[220:223], v[104:107]
	v_mfma_f32_16x16x32_bf16 v[92:95], v[142:145], v[228:231], v[92:95]
	v_mfma_f32_16x16x32_bf16 v[88:91], v[150:153], v[228:231], v[88:91]
	v_mfma_f32_16x16x32_bf16 v[76:79], v[142:145], v[236:239], v[76:79]
	v_mfma_f32_16x16x32_bf16 v[72:75], v[150:153], v[236:239], v[72:75]
	v_mfma_f32_16x16x32_bf16 v[124:127], v[146:149], v[216:219], v[124:127]
	v_mfma_f32_16x16x32_bf16 v[120:123], v[154:157], v[216:219], v[120:123]
	v_mfma_f32_16x16x32_bf16 v[108:111], v[146:149], v[224:227], v[108:111]
	v_mfma_f32_16x16x32_bf16 v[104:107], v[154:157], v[224:227], v[104:107]
	v_mfma_f32_16x16x32_bf16 v[92:95], v[146:149], v[232:235], v[92:95]
	v_mfma_f32_16x16x32_bf16 v[88:91], v[154:157], v[232:235], v[88:91]
	v_mfma_f32_16x16x32_bf16 v[76:79], v[146:149], v[240:243], v[76:79]
	v_mfma_f32_16x16x32_bf16 v[72:75], v[154:157], v[240:243], v[72:75]
	s_setprio 0
	s_setprio 1
	v_mfma_f32_16x16x32_bf16 v[116:119], v[188:191], v[212:215], v[116:119]
	v_mfma_f32_16x16x32_bf16 v[112:115], v[196:199], v[212:215], v[112:115]
	v_mfma_f32_16x16x32_bf16 v[100:103], v[188:191], v[220:223], v[100:103]
	v_mfma_f32_16x16x32_bf16 v[96:99], v[196:199], v[220:223], v[96:99]
	v_mfma_f32_16x16x32_bf16 v[84:87], v[188:191], v[228:231], v[84:87]
	v_mfma_f32_16x16x32_bf16 v[80:83], v[196:199], v[228:231], v[80:83]
	v_mfma_f32_16x16x32_bf16 v[68:71], v[188:191], v[236:239], v[68:71]
	v_mfma_f32_16x16x32_bf16 v[64:67], v[196:199], v[236:239], v[64:67]
	v_mfma_f32_16x16x32_bf16 v[116:119], v[192:195], v[216:219], v[116:119]
	v_mfma_f32_16x16x32_bf16 v[112:115], v[200:203], v[216:219], v[112:115]
	v_mfma_f32_16x16x32_bf16 v[100:103], v[192:195], v[224:227], v[100:103]
	v_mfma_f32_16x16x32_bf16 v[96:99], v[200:203], v[224:227], v[96:99]
	v_mfma_f32_16x16x32_bf16 v[84:87], v[192:195], v[232:235], v[84:87]
	v_mfma_f32_16x16x32_bf16 v[80:83], v[200:203], v[232:235], v[80:83]
	v_mfma_f32_16x16x32_bf16 v[68:71], v[192:195], v[240:243], v[68:71]
	v_mfma_f32_16x16x32_bf16 v[64:67], v[200:203], v[240:243], v[64:67]
	s_setprio 0
	s_barrier
	v_readfirstlane_b32 s47, v162
	v_lshl_add_u64 v[158:159], s[48:49], 0, v[164:165]
	s_mov_b32 m0, s47
	v_lshl_add_u64 v[244:245], s[48:49], 0, v[132:133]
	v_readfirstlane_b32 s47, v163
	s_add_u32 s48, s48, s66
	ds_read_b128 v[212:215], v187 offset:16384
	ds_read_b128 v[216:219], v187 offset:17408
	ds_read_b128 v[220:223], v187 offset:18432
	ds_read_b128 v[224:227], v187 offset:19456
	ds_read_b128 v[228:231], v187 offset:20480
	ds_read_b128 v[232:235], v187 offset:21504
	ds_read_b128 v[236:239], v187 offset:22528
	ds_read_b128 v[240:243], v187 offset:23552
	global_load_lds_dwordx4 v[158:159], off
	s_mov_b32 m0, s47
	s_addc_u32 s49, s49, 0
	v_readfirstlane_b32 s47, v170
	global_load_lds_dwordx4 v[244:245], off
	v_lshl_add_u64 v[246:247], s[48:49], 0, v[164:165]
	s_mov_b32 m0, s47
	v_readfirstlane_b32 s47, v171
	global_load_lds_dwordx4 v[246:247], off
	v_lshl_add_u64 v[248:249], s[48:49], 0, v[132:133]
	s_mov_b32 m0, s47
	v_readfirstlane_b32 s47, v172
	global_load_lds_dwordx4 v[248:249], off
	v_lshl_add_u64 v[250:251], s[16:17], 0, v[128:129]
	s_mov_b32 m0, s47
	v_readfirstlane_b32 s47, v173
	global_load_lds_dwordx4 v[250:251], off
	v_lshl_add_u64 v[252:253], s[16:17], 0, v[130:131]
	s_mov_b32 m0, s47
	s_nop 0
	global_load_lds_dwordx4 v[252:253], off
	s_waitcnt vmcnt(8)
	s_waitcnt lgkmcnt(0)
	s_barrier
; #define PG8_STAGE(bufoff, gbase, voff) do { _Pragma("unroll") for (int _i = 0; _i < 2; ++_i) \
;         __builtin_amdgcn_global_load_lds((const unsigned*)((const char*)(gbase) + (voff)[_i]), (PG8_LAS unsigned*)(lds + (bufoff) + ldsw + _i * 8192), 16, 0, 0); } while (0)
; #define PG8_LDA(dst, b, h) do { _Pragma("unroll") for (int m = 0; m < 4; ++m) _Pragma("unroll") for (int k = 0; k < 2; ++k) dst[m][k] = *(const PG8_LAS bf16x8*)(lds + PG8_SA(b, h) + aoff + m * 2048 + k * 1024); } while (0)
; #define PG8_LDB(dst, b, h) do { _Pragma("unroll") for (int n = 0; n < 2; ++n) _Pragma("unroll") for (int k = 0; k < 2; ++k) dst[n][k] = *(const PG8_LAS bf16x8*)(lds + PG8_SB(b, h) + boff + n * 2048 + k * 1024); } while (0)
; #define PG8_MMA(ai, bj, At, Bt) do { __builtin_amdgcn_s_setprio(1); _Pragma("unroll") for (int m = 0; m < 4; ++m) _Pragma("unroll") for (int n = 0; n < 2; ++n) _Pragma("unroll") for (int k = 0; k < 2; ++k) \
;         acc[ai][bj][m][n] = __builtin_amdgcn_mfma_f32_16x16x32_bf16(Bt[n][k], At[m][k], acc[ai][bj][m][n], 0, 0, 0); __builtin_amdgcn_s_setprio(0); } while (0)
; #define PG8_WAIT_V(n) asm volatile("s_waitcnt vmcnt(" #n ")" ::: "memory")
; #define PG8_WAIT_L(n) asm volatile("s_waitcnt lgkmcnt(" #n ")" ::: "memory")
; #define PG8_BAR __builtin_amdgcn_s_barrier()
; #define PG8_SCHED __builtin_amdgcn_sched_barrier(0)
; template <class Epi, class Sched, bool ALIGN_EPI = false, bool SP2 = false>
; __device__ __forceinline__ void gemm_phase(PG8_LAS unsigned char* lds, const Gemm g, const Sched& S, const Epi& E, const int tid) {
;     ...
;             PG8_WAIT_V(8); PG8_WAIT_L(0); PG8_BAR; PG8_MMA(0, 0, At, B0); PG8_MMA(0, 1, At, B1); PG8_BAR; PG8_SCHED;
;             PG8_LDA(At, 0, 1); PG8_STAGE(PG8_SB(0, 0), b2, voffB); PG8_STAGE(PG8_SB(0, 1), b2 + hstep, voffB); PG8_STAGE(PG8_SA(0, 0), a2, voffA);
;             PG8_WAIT_V(8); PG8_WAIT_L(0); PG8_BAR; PG8_MMA(1, 0, At, B0); PG8_MMA(1, 1, At, B1); PG8_BAR; PG8_SCHED;
;             PG8_LDB(B0, 1, 0); PG8_LDB(B1, 1, 1); PG8_SCHED; PG8_LDA(At, 1, 0); PG8_STAGE(PG8_SA(0, 1), a2 + hstep, voffA);
;             PG8_WAIT_V(8); PG8_WAIT_L(0); PG8_BAR; PG8_MMA(0, 0, At, B0); PG8_MMA(0, 1, At, B1); PG8_BAR; PG8_SCHED;
	s_setprio 1
	s_waitcnt lgkmcnt(0)
	v_mfma_f32_16x16x32_bf16 v[60:63], v[142:145], v[212:215], v[60:63]
	v_mfma_f32_16x16x32_bf16 v[56:59], v[150:153], v[212:215], v[56:59]
	v_mfma_f32_16x16x32_bf16 v[44:47], v[142:145], v[220:223], v[44:47]
	v_mfma_f32_16x16x32_bf16 v[40:43], v[150:153], v[220:223], v[40:43]
	v_mfma_f32_16x16x32_bf16 v[28:31], v[142:145], v[228:231], v[28:31]
	v_mfma_f32_16x16x32_bf16 v[24:27], v[150:153], v[228:231], v[24:27]
	v_mfma_f32_16x16x32_bf16 v[12:15], v[142:145], v[236:239], v[12:15]
	v_mfma_f32_16x16x32_bf16 v[8:11], v[150:153], v[236:239], v[8:11]
	v_mfma_f32_16x16x32_bf16 v[60:63], v[146:149], v[216:219], v[60:63]
	v_mfma_f32_16x16x32_bf16 v[56:59], v[154:157], v[216:219], v[56:59]
	v_mfma_f32_16x16x32_bf16 v[44:47], v[146:149], v[224:227], v[44:47]
	v_mfma_f32_16x16x32_bf16 v[40:43], v[154:157], v[224:227], v[40:43]
	v_mfma_f32_16x16x32_bf16 v[28:31], v[146:149], v[232:235], v[28:31]
	v_mfma_f32_16x16x32_bf16 v[24:27], v[154:157], v[232:235], v[24:27]
	v_mfma_f32_16x16x32_bf16 v[12:15], v[146:149], v[240:243], v[12:15]
	v_mfma_f32_16x16x32_bf16 v[8:11], v[154:157], v[240:243], v[8:11]
	s_setprio 0
	s_setprio 1
	v_mfma_f32_16x16x32_bf16 v[52:55], v[188:191], v[212:215], v[52:55]
	v_mfma_f32_16x16x32_bf16 v[48:51], v[196:199], v[212:215], v[48:51]
	v_mfma_f32_16x16x32_bf16 v[36:39], v[188:191], v[220:223], v[36:39]
	v_mfma_f32_16x16x32_bf16 v[32:35], v[196:199], v[220:223], v[32:35]
	v_mfma_f32_16x16x32_bf16 v[20:23], v[188:191], v[228:231], v[20:23]
	v_mfma_f32_16x16x32_bf16 v[16:19], v[196:199], v[228:231], v[16:19]
	v_mfma_f32_16x16x32_bf16 v[4:7], v[188:191], v[236:239], v[4:7]
	v_mfma_f32_16x16x32_bf16 v[0:3], v[196:199], v[236:239], v[0:3]
	v_mfma_f32_16x16x32_bf16 v[52:55], v[192:195], v[216:219], v[52:55]
	v_mfma_f32_16x16x32_bf16 v[48:51], v[200:203], v[216:219], v[48:51]
	v_mfma_f32_16x16x32_bf16 v[36:39], v[192:195], v[224:227], v[36:39]
	v_mfma_f32_16x16x32_bf16 v[32:35], v[200:203], v[224:227], v[32:35]
	v_mfma_f32_16x16x32_bf16 v[20:23], v[192:195], v[232:235], v[20:23]
	v_mfma_f32_16x16x32_bf16 v[16:19], v[200:203], v[232:235], v[16:19]
	v_mfma_f32_16x16x32_bf16 v[4:7], v[192:195], v[240:243], v[4:7]
	v_mfma_f32_16x16x32_bf16 v[0:3], v[200:203], v[240:243], v[0:3]
	s_setprio 0
	s_barrier
	v_add_u32_e32 v135, v176, v186
	ds_read_b128 v[142:145], v135
	ds_read_b128 v[146:149], v135 offset:1024
	ds_read_b128 v[150:153], v135 offset:2048
	ds_read_b128 v[154:157], v135 offset:3072
	v_add_u32_e32 v135, v181, v186
	ds_read_b128 v[188:191], v135
	ds_read_b128 v[192:195], v135 offset:1024
	ds_read_b128 v[196:199], v135 offset:2048
	ds_read_b128 v[200:203], v135 offset:3072
	s_add_u32 s16, s16, s66
	s_addc_u32 s17, s17, 0
	v_readfirstlane_b32 s47, v174
	v_lshl_add_u64 v[208:209], s[16:17], 0, v[128:129]
	s_mov_b32 m0, s47
	ds_read_b128 v[212:215], v187 offset:32768
	ds_read_b128 v[216:219], v187 offset:33792
	ds_read_b128 v[220:223], v187 offset:34816
	ds_read_b128 v[224:227], v187 offset:35840
	ds_read_b128 v[228:231], v187 offset:36864
	ds_read_b128 v[232:235], v187 offset:37888
	ds_read_b128 v[236:239], v187 offset:38912
	ds_read_b128 v[240:243], v187 offset:39936
	global_load_lds_dwordx4 v[208:209], off
	v_lshl_add_u64 v[208:209], s[16:17], 0, v[130:131]
	v_readfirstlane_b32 s16, v175
	s_mov_b32 m0, s16
	s_nop 0
	global_load_lds_dwordx4 v[208:209], off
	s_waitcnt vmcnt(8)
	s_waitcnt lgkmcnt(0)
	s_barrier
	s_setprio 1
	s_waitcnt lgkmcnt(0)
	v_mfma_f32_16x16x32_bf16 v[124:127], v[142:145], v[212:215], v[124:127]
	v_mfma_f32_16x16x32_bf16 v[120:123], v[150:153], v[212:215], v[120:123]
	v_mfma_f32_16x16x32_bf16 v[108:111], v[142:145], v[220:223], v[108:111]
	v_mfma_f32_16x16x32_bf16 v[104:107], v[150:153], v[220:223], v[104:107]
	v_mfma_f32_16x16x32_bf16 v[92:95], v[142:145], v[228:231], v[92:95]
	v_mfma_f32_16x16x32_bf16 v[88:91], v[150:153], v[228:231], v[88:91]
	v_mfma_f32_16x16x32_bf16 v[76:79], v[142:145], v[236:239], v[76:79]
	v_mfma_f32_16x16x32_bf16 v[72:75], v[150:153], v[236:239], v[72:75]
	v_mfma_f32_16x16x32_bf16 v[124:127], v[146:149], v[216:219], v[124:127]
	v_mfma_f32_16x16x32_bf16 v[120:123], v[154:157], v[216:219], v[120:123]
	v_mfma_f32_16x16x32_bf16 v[108:111], v[146:149], v[224:227], v[108:111]
	v_mfma_f32_16x16x32_bf16 v[104:107], v[154:157], v[224:227], v[104:107]
	v_mfma_f32_16x16x32_bf16 v[92:95], v[146:149], v[232:235], v[92:95]
	v_mfma_f32_16x16x32_bf16 v[88:91], v[154:157], v[232:235], v[88:91]
	v_mfma_f32_16x16x32_bf16 v[76:79], v[146:149], v[240:243], v[76:79]
	v_mfma_f32_16x16x32_bf16 v[72:75], v[154:157], v[240:243], v[72:75]
	s_setprio 0
	s_setprio 1
	v_mfma_f32_16x16x32_bf16 v[116:119], v[188:191], v[212:215], v[116:119]
	v_mfma_f32_16x16x32_bf16 v[112:115], v[196:199], v[212:215], v[112:115]
	v_mfma_f32_16x16x32_bf16 v[100:103], v[188:191], v[220:223], v[100:103]
	v_mfma_f32_16x16x32_bf16 v[96:99], v[196:199], v[220:223], v[96:99]
	v_mfma_f32_16x16x32_bf16 v[84:87], v[188:191], v[228:231], v[84:87]
	v_mfma_f32_16x16x32_bf16 v[80:83], v[196:199], v[228:231], v[80:83]
	v_mfma_f32_16x16x32_bf16 v[68:71], v[188:191], v[236:239], v[68:71]
	v_mfma_f32_16x16x32_bf16 v[64:67], v[196:199], v[236:239], v[64:67]
	v_mfma_f32_16x16x32_bf16 v[116:119], v[192:195], v[216:219], v[116:119]
	v_mfma_f32_16x16x32_bf16 v[112:115], v[200:203], v[216:219], v[112:115]
	v_mfma_f32_16x16x32_bf16 v[100:103], v[192:195], v[224:227], v[100:103]
	v_mfma_f32_16x16x32_bf16 v[96:99], v[200:203], v[224:227], v[96:99]
	v_mfma_f32_16x16x32_bf16 v[84:87], v[192:195], v[232:235], v[84:87]
	v_mfma_f32_16x16x32_bf16 v[80:83], v[200:203], v[232:235], v[80:83]
	v_mfma_f32_16x16x32_bf16 v[68:71], v[192:195], v[240:243], v[68:71]
	v_mfma_f32_16x16x32_bf16 v[64:67], v[200:203], v[240:243], v[64:67]
	s_setprio 0
	s_barrier
; #define PG8_STAGE(bufoff, gbase, voff) do { _Pragma("unroll") for (int _i = 0; _i < 2; ++_i) \
;         __builtin_amdgcn_global_load_lds((const unsigned*)((const char*)(gbase) + (voff)[_i]), (PG8_LAS unsigned*)(lds + (bufoff) + ldsw + _i * 8192), 16, 0, 0); } while (0)
; #define PG8_LDA(dst, b, h) do { _Pragma("unroll") for (int m = 0; m < 4; ++m) _Pragma("unroll") for (int k = 0; k < 2; ++k) dst[m][k] = *(const PG8_LAS bf16x8*)(lds + PG8_SA(b, h) + aoff + m * 2048 + k * 1024); } while (0)
; #define PG8_MMA(ai, bj, At, Bt) do { __builtin_amdgcn_s_setprio(1); _Pragma("unroll") for (int m = 0; m < 4; ++m) _Pragma("unroll") for (int n = 0; n < 2; ++n) _Pragma("unroll") for (int k = 0; k < 2; ++k) \
;         acc[ai][bj][m][n] = __builtin_amdgcn_mfma_f32_16x16x32_bf16(Bt[n][k], At[m][k], acc[ai][bj][m][n], 0, 0, 0); __builtin_amdgcn_s_setprio(0); } while (0)
; #define PG8_WAIT_V(n) asm volatile("s_waitcnt vmcnt(" #n ")" ::: "memory")
; #define PG8_WAIT_L(n) asm volatile("s_waitcnt lgkmcnt(" #n ")" ::: "memory")
; #define PG8_BAR __builtin_amdgcn_s_barrier()
; #define PG8_SCHED __builtin_amdgcn_sched_barrier(0)
; template <class Epi, class Sched, bool ALIGN_EPI = false, bool SP2 = false>
; __device__ __forceinline__ void gemm_phase(PG8_LAS unsigned char* lds, const Gemm g, const Sched& S, const Epi& E, const int tid) {
;     ...
;             PG8_LDA(At, 1, 1); PG8_STAGE(PG8_SB(1, 0), b3, voffB); PG8_STAGE(PG8_SB(1, 1), b3 + hstep, voffB); PG8_STAGE(PG8_SA(1, 0), a3, voffA);
;             PG8_WAIT_V(8); PG8_WAIT_L(0); PG8_BAR; PG8_MMA(1, 0, At, B0); PG8_MMA(1, 1, At, B1); PG8_BAR; PG8_SCHED;
	v_readfirstlane_b32 s16, v177
	v_lshl_add_u64 v[158:159], v[158:159], 0, s[76:77]
	s_mov_b32 m0, s16
	v_readfirstlane_b32 s16, v178
	ds_read_b128 v[212:215], v187 offset:49152
	ds_read_b128 v[216:219], v187 offset:50176
	ds_read_b128 v[220:223], v187 offset:51200
	ds_read_b128 v[224:227], v187 offset:52224
	ds_read_b128 v[228:231], v187 offset:53248
	ds_read_b128 v[232:235], v187 offset:54272
	ds_read_b128 v[236:239], v187 offset:55296
	ds_read_b128 v[240:243], v187 offset:56320
	global_load_lds_dwordx4 v[158:159], off
	v_lshl_add_u64 v[158:159], v[244:245], 0, s[76:77]
	s_mov_b32 m0, s16
	v_readfirstlane_b32 s16, v182
	global_load_lds_dwordx4 v[158:159], off
	v_lshl_add_u64 v[158:159], v[246:247], 0, s[76:77]
	s_mov_b32 m0, s16
	v_readfirstlane_b32 s16, v183
	global_load_lds_dwordx4 v[158:159], off
	v_lshl_add_u64 v[158:159], v[248:249], 0, s[76:77]
	s_mov_b32 m0, s16
	v_readfirstlane_b32 s16, v179
	global_load_lds_dwordx4 v[158:159], off
	v_lshl_add_u64 v[158:159], v[250:251], 0, s[76:77]
	s_mov_b32 m0, s16
	v_readfirstlane_b32 s16, v180
	global_load_lds_dwordx4 v[158:159], off
	v_lshl_add_u64 v[158:159], v[252:253], 0, s[76:77]
	s_mov_b32 m0, s16
	s_nop 0
	global_load_lds_dwordx4 v[158:159], off
	s_waitcnt vmcnt(8)
	s_waitcnt lgkmcnt(0)
	s_barrier
	s_setprio 1
	s_waitcnt lgkmcnt(0)
	v_mfma_f32_16x16x32_bf16 v[60:63], v[142:145], v[212:215], v[60:63]
	v_mfma_f32_16x16x32_bf16 v[56:59], v[150:153], v[212:215], v[56:59]
	v_mfma_f32_16x16x32_bf16 v[44:47], v[142:145], v[220:223], v[44:47]
	v_mfma_f32_16x16x32_bf16 v[40:43], v[150:153], v[220:223], v[40:43]
	v_mfma_f32_16x16x32_bf16 v[28:31], v[142:145], v[228:231], v[28:31]
	v_mfma_f32_16x16x32_bf16 v[24:27], v[150:153], v[228:231], v[24:27]
	v_mfma_f32_16x16x32_bf16 v[12:15], v[142:145], v[236:239], v[12:15]
	v_mfma_f32_16x16x32_bf16 v[8:11], v[150:153], v[236:239], v[8:11]
	v_mfma_f32_16x16x32_bf16 v[60:63], v[146:149], v[216:219], v[60:63]
	v_mfma_f32_16x16x32_bf16 v[56:59], v[154:157], v[216:219], v[56:59]
	v_mfma_f32_16x16x32_bf16 v[44:47], v[146:149], v[224:227], v[44:47]
	v_mfma_f32_16x16x32_bf16 v[40:43], v[154:157], v[224:227], v[40:43]
	v_mfma_f32_16x16x32_bf16 v[28:31], v[146:149], v[232:235], v[28:31]
	v_mfma_f32_16x16x32_bf16 v[24:27], v[154:157], v[232:235], v[24:27]
	v_mfma_f32_16x16x32_bf16 v[12:15], v[146:149], v[240:243], v[12:15]
	v_mfma_f32_16x16x32_bf16 v[8:11], v[154:157], v[240:243], v[8:11]
	s_setprio 0
	s_setprio 1
	v_mfma_f32_16x16x32_bf16 v[52:55], v[188:191], v[212:215], v[52:55]
	v_mfma_f32_16x16x32_bf16 v[48:51], v[196:199], v[212:215], v[48:51]
	v_mfma_f32_16x16x32_bf16 v[36:39], v[188:191], v[220:223], v[36:39]
	v_mfma_f32_16x16x32_bf16 v[32:35], v[196:199], v[220:223], v[32:35]
	v_mfma_f32_16x16x32_bf16 v[20:23], v[188:191], v[228:231], v[20:23]
	v_mfma_f32_16x16x32_bf16 v[16:19], v[196:199], v[228:231], v[16:19]
	v_mfma_f32_16x16x32_bf16 v[4:7], v[188:191], v[236:239], v[4:7]
	v_mfma_f32_16x16x32_bf16 v[0:3], v[196:199], v[236:239], v[0:3]
	v_mfma_f32_16x16x32_bf16 v[52:55], v[192:195], v[216:219], v[52:55]
	v_mfma_f32_16x16x32_bf16 v[48:51], v[200:203], v[216:219], v[48:51]
	v_mfma_f32_16x16x32_bf16 v[36:39], v[192:195], v[224:227], v[36:39]
	v_mfma_f32_16x16x32_bf16 v[32:35], v[200:203], v[224:227], v[32:35]
	v_mfma_f32_16x16x32_bf16 v[20:23], v[192:195], v[232:235], v[20:23]
	v_mfma_f32_16x16x32_bf16 v[16:19], v[200:203], v[232:235], v[16:19]
	v_mfma_f32_16x16x32_bf16 v[4:7], v[192:195], v[240:243], v[4:7]
	v_mfma_f32_16x16x32_bf16 v[0:3], v[200:203], v[240:243], v[0:3]
	s_setprio 0
	s_barrier
	s_add_u32 s14, s14, 0x100
	s_addc_u32 s15, s15, 0
	s_add_u32 s44, s44, 0x100
	s_addc_u32 s45, s45, 0
	s_cmp_ge_u32 s46, s34
	s_mov_b32 s16, s46
	s_cbranch_scc0 .LBB0_765
	s_ashr_i32 s14, s42, 3
	s_lshl_b32 s16, s42, 8
	s_mul_hi_i32 s15, s14, 0x9000
	s_mul_i32 s14, s14, 0x9000
	s_add_u32 s14, s30, s14
	s_addc_u32 s15, s31, s15
	s_lshl_b32 s17, s43, 8
	v_mov_b32_e32 v192, v185
	v_mov_b32_e32 v135, v184
	s_or_b32 s17, s17, s36
	s_add_i32 s16, s16, s35
	v_lshl_add_u32 v158, v135, 3, s17
	v_ashrrev_i32_e32 v159, 31, v158
	v_lshl_add_u64 v[154:155], v[158:159], 2, s[14:15]
	global_load_dwordx4 v[150:153], v[154:155], off offset:16
	global_load_dwordx4 v[142:145], v[154:155], off
	global_load_dwordx4 v[228:231], v[154:155], off offset:528
	global_load_dwordx4 v[232:235], v[154:155], off offset:512
	v_mov_b32_e32 v135, v134
	s_and_b64 vcc, exec, s[6:7]
	s_mov_b32 s43, s40
	s_mov_b32 s42, s41
	v_add_u32_e32 v188, s16, v192
	v_ashrrev_i32_e32 v189, 31, v188
	v_lshlrev_b64 v[188:189], 10, v[188:189]
	v_lshl_add_u64 v[158:159], v[188:189], 0, v[158:159]
	v_lshlrev_b64 v[158:159], 2, v[158:159]
	s_mov_b64 s[16:17], s[10:11]
	v_lshl_add_u64 v[200:201], s[18:19], 0, v[158:159]
	global_load_dwordx4 v[188:191], v[200:201], off offset:16
	global_load_dwordx4 v[192:195], v[200:201], off
	global_load_dwordx4 v[196:199], v[200:201], off offset:528
	s_nop 0
	global_load_dwordx4 v[200:203], v[200:201], off offset:512
	v_lshl_add_u64 v[224:225], v[158:159], 0, s[86:87]
	v_lshl_add_u64 v[224:225], s[18:19], 0, v[224:225]
	global_load_dwordx4 v[212:215], v[224:225], off offset:16
	global_load_dwordx4 v[216:219], v[224:225], off
	global_load_dwordx4 v[220:223], v[224:225], off offset:528
	s_nop 0
	global_load_dwordx4 v[224:227], v[224:225], off offset:512
	s_waitcnt vmcnt(8)
	v_pk_mul_f32 v[146:147], v[134:135], v[144:145]
	v_pk_mul_f32 v[148:149], v[136:137], v[142:143]
	v_pk_mul_f32 v[142:143], v[134:135], v[152:153]
	v_pk_mul_f32 v[144:145], v[136:137], v[150:151]
	v_pk_mul_f32 v[154:155], v[134:135], v[234:235]
	v_pk_mul_f32 v[152:153], v[136:137], v[228:229]
	v_pk_mul_f32 v[156:157], v[136:137], v[232:233]
	v_pk_mul_f32 v[150:151], v[134:135], v[230:231]
	v_lshl_add_u64 v[240:241], v[158:159], 0, s[74:75]
	v_lshl_add_u64 v[240:241], s[18:19], 0, v[240:241]
	global_load_dwordx4 v[228:231], v[240:241], off offset:16
	global_load_dwordx4 v[232:235], v[240:241], off
	global_load_dwordx4 v[236:239], v[240:241], off offset:528
	s_nop 0
	global_load_dwordx4 v[240:243], v[240:241], off offset:512
	s_waitcnt vmcnt(8)
	v_pk_fma_f32 v[122:123], v[122:123], v[142:143], v[190:191]
	v_pk_fma_f32 v[126:127], v[126:127], v[146:147], v[194:195]
	v_pk_fma_f32 v[124:125], v[124:125], v[148:149], v[192:193]
	v_pk_fma_f32 v[120:121], v[120:121], v[144:145], v[188:189]
	v_pk_fma_f32 v[118:119], v[118:119], v[154:155], v[202:203]
	v_pk_fma_f32 v[116:117], v[116:117], v[156:157], v[200:201]
	v_pk_fma_f32 v[114:115], v[114:115], v[150:151], v[198:199]
	v_pk_fma_f32 v[112:113], v[112:113], v[152:153], v[196:197]
	v_lshl_add_u64 v[188:189], s[12:13], 0, v[158:159]
	global_store_dwordx4 v[188:189], v[124:127], off
	global_store_dwordx4 v[188:189], v[120:123], off offset:16
	global_store_dwordx4 v[188:189], v[116:119], off offset:512
	global_store_dwordx4 v[188:189], v[112:115], off offset:528
	s_mov_b64 s[14:15], 0x30000
	v_lshl_add_u64 v[200:201], v[158:159], 0, s[14:15]
	v_lshl_add_u64 v[200:201], s[18:19], 0, v[200:201]
	global_load_dwordx4 v[188:191], v[200:201], off offset:16
	global_load_dwordx4 v[192:195], v[200:201], off
	global_load_dwordx4 v[196:199], v[200:201], off offset:528
	s_nop 0
	global_load_dwordx4 v[200:203], v[200:201], off offset:512
	s_waitcnt vmcnt(12)
	v_pk_fma_f32 v[106:107], v[106:107], v[142:143], v[214:215]
	v_pk_fma_f32 v[110:111], v[110:111], v[146:147], v[218:219]
	v_pk_fma_f32 v[108:109], v[108:109], v[148:149], v[216:217]
	v_pk_fma_f32 v[104:105], v[104:105], v[144:145], v[212:213]
	v_pk_fma_f32 v[102:103], v[102:103], v[154:155], v[226:227]
	v_pk_fma_f32 v[100:101], v[100:101], v[156:157], v[224:225]
	v_pk_fma_f32 v[98:99], v[98:99], v[150:151], v[222:223]
	v_pk_fma_f32 v[96:97], v[96:97], v[152:153], v[220:221]
	v_lshl_add_u64 v[212:213], v[158:159], 0, s[86:87]
	v_lshl_add_u64 v[212:213], s[12:13], 0, v[212:213]
	global_store_dwordx4 v[212:213], v[108:111], off
	global_store_dwordx4 v[212:213], v[104:107], off offset:16
	global_store_dwordx4 v[212:213], v[100:103], off offset:512
	global_store_dwordx4 v[212:213], v[96:99], off offset:528
	s_mov_b64 s[14:15], 0x80000
	v_lshl_add_u64 v[224:225], v[158:159], 0, s[14:15]
	v_lshl_add_u64 v[224:225], s[18:19], 0, v[224:225]
	global_load_dwordx4 v[212:215], v[224:225], off offset:16
	global_load_dwordx4 v[216:219], v[224:225], off
	global_load_dwordx4 v[220:223], v[224:225], off offset:528
	s_nop 0
	global_load_dwordx4 v[224:227], v[224:225], off offset:512
	s_waitcnt vmcnt(16)
	v_pk_fma_f32 v[90:91], v[90:91], v[142:143], v[230:231]
	v_pk_fma_f32 v[94:95], v[94:95], v[146:147], v[234:235]
	v_pk_fma_f32 v[92:93], v[92:93], v[148:149], v[232:233]
	v_pk_fma_f32 v[88:89], v[88:89], v[144:145], v[228:229]
	v_pk_fma_f32 v[86:87], v[86:87], v[154:155], v[242:243]
	v_pk_fma_f32 v[84:85], v[84:85], v[156:157], v[240:241]
	v_pk_fma_f32 v[82:83], v[82:83], v[150:151], v[238:239]
	v_pk_fma_f32 v[80:81], v[80:81], v[152:153], v[236:237]
	v_lshl_add_u64 v[228:229], v[158:159], 0, s[74:75]
	v_lshl_add_u64 v[228:229], s[12:13], 0, v[228:229]
	global_store_dwordx4 v[228:229], v[92:95], off
	global_store_dwordx4 v[228:229], v[88:91], off offset:16
	global_store_dwordx4 v[228:229], v[84:87], off offset:512
	global_store_dwordx4 v[228:229], v[80:83], off offset:528
	s_mov_b64 s[14:15], 0x90000
	v_lshl_add_u64 v[240:241], v[158:159], 0, s[14:15]
	v_lshl_add_u64 v[240:241], s[18:19], 0, v[240:241]
	global_load_dwordx4 v[228:231], v[240:241], off offset:16
	global_load_dwordx4 v[232:235], v[240:241], off
	global_load_dwordx4 v[236:239], v[240:241], off offset:528
	s_nop 0
	global_load_dwordx4 v[240:243], v[240:241], off offset:512
	s_waitcnt vmcnt(16)
; #define PG8_WAIT_V(n) asm volatile("s_waitcnt vmcnt(" #n ")" ::: "memory")
; #define PG8_BAR __builtin_amdgcn_s_barrier()
; template <class Epi, class Sched, bool ALIGN_EPI = false, bool SP2 = false>
; __device__ __forceinline__ void gemm_phase(PG8_LAS unsigned char* lds, const Gemm g, const Sched& S, const Epi& E, const int tid) {
;     ...
;         cur = nxt; cA = nA; cB = nB; ++ui;
;         if constexpr (ALIGN_EPI) { if (wr == 1) PG8_BAR; }
;     }
;     PG8_WAIT_V(0);
;     if constexpr (!ALIGN_EPI) { if (wr == 0) PG8_BAR; }
;     PG8_BAR;
	v_pk_fma_f32 v[74:75], v[74:75], v[142:143], v[190:191]
	v_pk_fma_f32 v[78:79], v[78:79], v[146:147], v[194:195]
	v_pk_fma_f32 v[76:77], v[76:77], v[148:149], v[192:193]
	v_pk_fma_f32 v[72:73], v[72:73], v[144:145], v[188:189]
	v_pk_fma_f32 v[70:71], v[70:71], v[154:155], v[202:203]
	v_pk_fma_f32 v[68:69], v[68:69], v[156:157], v[200:201]
	v_pk_fma_f32 v[66:67], v[66:67], v[150:151], v[198:199]
	v_pk_fma_f32 v[64:65], v[64:65], v[152:153], v[196:197]
	s_mov_b64 s[14:15], 0x30000
	v_lshl_add_u64 v[188:189], v[158:159], 0, s[14:15]
	v_lshl_add_u64 v[188:189], s[12:13], 0, v[188:189]
	global_store_dwordx4 v[188:189], v[76:79], off
	global_store_dwordx4 v[188:189], v[72:75], off offset:16
	global_store_dwordx4 v[188:189], v[68:71], off offset:512
	global_store_dwordx4 v[188:189], v[64:67], off offset:528
	s_mov_b64 s[14:15], 0xa0000
	v_lshl_add_u64 v[200:201], v[158:159], 0, s[14:15]
	v_lshl_add_u64 v[200:201], s[18:19], 0, v[200:201]
	global_load_dwordx4 v[188:191], v[200:201], off offset:16
	global_load_dwordx4 v[192:195], v[200:201], off
	global_load_dwordx4 v[196:199], v[200:201], off offset:528
	s_nop 0
	global_load_dwordx4 v[200:203], v[200:201], off offset:512
	s_waitcnt vmcnt(16)
	v_pk_fma_f32 v[58:59], v[58:59], v[142:143], v[214:215]
	v_pk_fma_f32 v[62:63], v[62:63], v[146:147], v[218:219]
	v_pk_fma_f32 v[60:61], v[60:61], v[148:149], v[216:217]
	v_pk_fma_f32 v[56:57], v[56:57], v[144:145], v[212:213]
	v_pk_fma_f32 v[54:55], v[54:55], v[154:155], v[226:227]
	v_pk_fma_f32 v[52:53], v[52:53], v[156:157], v[224:225]
	v_pk_fma_f32 v[50:51], v[50:51], v[150:151], v[222:223]
	v_pk_fma_f32 v[48:49], v[48:49], v[152:153], v[220:221]
	s_mov_b64 s[14:15], 0x80000
	v_lshl_add_u64 v[212:213], v[158:159], 0, s[14:15]
	v_lshl_add_u64 v[212:213], s[12:13], 0, v[212:213]
	global_store_dwordx4 v[212:213], v[60:63], off
	global_store_dwordx4 v[212:213], v[56:59], off offset:16
	global_store_dwordx4 v[212:213], v[52:55], off offset:512
	global_store_dwordx4 v[212:213], v[48:51], off offset:528
	s_mov_b64 s[14:15], 0xb0000
	v_lshl_add_u64 v[224:225], v[158:159], 0, s[14:15]
	v_lshl_add_u64 v[224:225], s[18:19], 0, v[224:225]
	global_load_dwordx4 v[212:215], v[224:225], off offset:16
	global_load_dwordx4 v[216:219], v[224:225], off
	global_load_dwordx4 v[220:223], v[224:225], off offset:528
	s_nop 0
	global_load_dwordx4 v[224:227], v[224:225], off offset:512
	s_waitcnt vmcnt(16)
	v_pk_fma_f32 v[42:43], v[42:43], v[142:143], v[230:231]
	v_pk_fma_f32 v[46:47], v[46:47], v[146:147], v[234:235]
	v_pk_fma_f32 v[44:45], v[44:45], v[148:149], v[232:233]
	v_pk_fma_f32 v[40:41], v[40:41], v[144:145], v[228:229]
	v_pk_fma_f32 v[38:39], v[38:39], v[154:155], v[242:243]
	v_pk_fma_f32 v[36:37], v[36:37], v[156:157], v[240:241]
	v_pk_fma_f32 v[34:35], v[34:35], v[150:151], v[238:239]
	v_pk_fma_f32 v[32:33], v[32:33], v[152:153], v[236:237]
	s_mov_b64 s[14:15], 0x90000
	v_lshl_add_u64 v[228:229], v[158:159], 0, s[14:15]
	v_lshl_add_u64 v[228:229], s[12:13], 0, v[228:229]
	global_store_dwordx4 v[228:229], v[44:47], off
	global_store_dwordx4 v[228:229], v[40:43], off offset:16
	global_store_dwordx4 v[228:229], v[36:39], off offset:512
	global_store_dwordx4 v[228:229], v[32:35], off offset:528
	s_waitcnt vmcnt(12)
	v_pk_fma_f32 v[26:27], v[26:27], v[142:143], v[190:191]
	v_pk_fma_f32 v[30:31], v[30:31], v[146:147], v[194:195]
	v_pk_fma_f32 v[28:29], v[28:29], v[148:149], v[192:193]
	v_pk_fma_f32 v[24:25], v[24:25], v[144:145], v[188:189]
	v_pk_fma_f32 v[22:23], v[22:23], v[154:155], v[202:203]
	v_pk_fma_f32 v[20:21], v[20:21], v[156:157], v[200:201]
	v_pk_fma_f32 v[18:19], v[18:19], v[150:151], v[198:199]
	v_pk_fma_f32 v[16:17], v[16:17], v[152:153], v[196:197]
	s_mov_b64 s[14:15], 0xa0000
	v_lshl_add_u64 v[188:189], v[158:159], 0, s[14:15]
	v_lshl_add_u64 v[188:189], s[12:13], 0, v[188:189]
	global_store_dwordx4 v[188:189], v[28:31], off
	global_store_dwordx4 v[188:189], v[24:27], off offset:16
	global_store_dwordx4 v[188:189], v[20:23], off offset:512
	global_store_dwordx4 v[188:189], v[16:19], off offset:528
	s_waitcnt vmcnt(8)
	v_pk_fma_f32 v[10:11], v[10:11], v[142:143], v[214:215]
	v_pk_fma_f32 v[14:15], v[14:15], v[146:147], v[218:219]
	v_pk_fma_f32 v[12:13], v[12:13], v[148:149], v[216:217]
	v_pk_fma_f32 v[8:9], v[8:9], v[144:145], v[212:213]
	v_pk_fma_f32 v[6:7], v[6:7], v[154:155], v[226:227]
	v_pk_fma_f32 v[4:5], v[4:5], v[156:157], v[224:225]
	v_pk_fma_f32 v[2:3], v[2:3], v[150:151], v[222:223]
	v_pk_fma_f32 v[0:1], v[0:1], v[152:153], v[220:221]
	s_mov_b64 s[14:15], 0xb0000
	v_lshl_add_u64 v[212:213], v[158:159], 0, s[14:15]
	v_lshl_add_u64 v[212:213], s[12:13], 0, v[212:213]
	global_store_dwordx4 v[212:213], v[12:15], off
	global_store_dwordx4 v[212:213], v[8:11], off offset:16
	global_store_dwordx4 v[212:213], v[4:7], off offset:512
	global_store_dwordx4 v[212:213], v[0:3], off offset:528
	s_mov_b64 s[14:15], s[8:9]
	s_cbranch_vccz .LBB0_754
	s_waitcnt vmcnt(0)
	s_cmpk_gt_u32 s4, 0xff
	s_cbranch_scc1 .LBB0_769
	s_barrier
